# conv_fixup body rewritten with wide accesses: each thread owns 4 adjacent columns (dwordx4 loads, dwordx2 stores) instead of 6 strided single columns (60 dword loads, 12 short stores per unit); same f
# baseline (speedup 1.0000x reference)
; __device__ __forceinline__ unsigned cvt_pk_bf16(float lo, float hi) { const f32x2 v = {lo, hi}; const bf16x2_t b = __builtin_convertvector(v, bf16x2_t); return __builtin_bit_cast(unsigned, b); }
; __device__ __forceinline__ float silu_f(float c) { return c * __builtin_amdgcn_rcpf(1.f + __builtin_amdgcn_exp2f(-c * LOG2E)); }
; template <class Sched> __device__ __forceinline__ void conv_fixup(const Sched& S, bf16_t* U, const float* bot, const float* topa, const float* topv, const float* cw, const float* cb) {
;     ...
;     for (int i = 0; S.next(i, u); ++i) {
;         if ((u.pm & 31) == 0) continue;
;         float v[NIT][10];
; #pragma unroll
;         for (int k = 0; k < NIT; ++k) {
;             const int f = min(tid + 512 * k, FF - 1);
;             v[k][0] = bot[(size_t)((u.pm - 1) * 2) * FF + f]; v[k][1] = bot[(size_t)((u.pm - 1) * 2 + 1) * FF + f];
;             v[k][2] = topa[(size_t)(u.pm * 2) * FF + f]; v[k][3] = topa[(size_t)(u.pm * 2 + 1) * FF + f];
;             v[k][4] = topv[(size_t)(u.pm * 2) * FF + f]; v[k][5] = topv[(size_t)(u.pm * 2 + 1) * FF + f];
;             v[k][6] = cw[f]; v[k][7] = cw[FF + f]; v[k][8] = cw[2 * FF + f]; v[k][9] = cb[f];
;         }
; #pragma unroll
;         for (int k = 0; k < NIT; ++k) {
;             const int f = tid + 512 * k;
;             const float c0 = v[k][0] * v[k][6] + v[k][1] * v[k][7] + v[k][2] * v[k][8] + v[k][9], c1 = v[k][1] * v[k][6] + v[k][2] * v[k][7] + v[k][3] * v[k][8] + v[k][9];
;             const unsigned r0 = cvt_pk_bf16(silu_f(c0) * v[k][4], 0.f), r1 = cvt_pk_bf16(silu_f(c1) * v[k][5], 0.f);
;             if (f < FF) { U[(size_t)(u.pm * 256) * FF + f] = (bf16_t)(r0 & 0xffffu); U[(size_t)(u.pm * 256 + 1) * FF + f] = (bf16_t)(r1 & 0xffffu); }
;         }
.LBB0_304:
	s_ashr_i32 s8, s8, 3
	s_add_i32 s8, s20, s8
	s_ashr_i32 s9, s8, 31
	s_lshr_b32 s9, s9, 27
	s_add_i32 s9, s8, s9
	s_ashr_i32 s18, s9, 5
	s_lshl_b32 s18, s18, 3
	s_sub_i32 s19, 0x80, s18
	s_min_i32 s19, s19, 8
	s_abs_i32 s19, s19
	s_waitcnt vmcnt(39)
	v_cvt_f32_u32_e32 v1, s19
	s_sub_i32 s20, 0, s19
	s_andn2_b32 s9, s9, 31
	s_sub_i32 s8, s8, s9
	v_rcp_iflag_f32_e32 v1, v1
	s_ashr_i32 s9, s8, 31
	s_abs_i32 s8, s8
	v_mul_f32_e32 v1, 0x4f7ffffe, v1
	v_cvt_u32_f32_e32 v1, v1
	s_nop 0
	v_readfirstlane_b32 s21, v1
	s_mul_i32 s20, s20, s21
	s_mul_hi_u32 s20, s21, s20
	s_add_i32 s21, s21, s20
	s_mul_hi_u32 s20, s8, s21
	s_mul_i32 s20, s20, s19
	s_sub_i32 s8, s8, s20
	s_sub_i32 s20, s8, s19
	s_cmp_ge_u32 s8, s19
	s_cselect_b32 s8, s20, s8
	s_sub_i32 s20, s8, s19
	s_cmp_ge_u32 s8, s19
	s_cselect_b32 s8, s20, s8
	s_xor_b32 s8, s8, s9
	s_sub_i32 s8, s8, s9
	s_add_i32 s8, s18, s8
	s_and_b32 s9, s8, 31
	s_cmp_eq_u32 s9, 0
	s_cbranch_scc1 .LBB0_297
	s_lshl_b32 s9, s8, 1
	s_mul_i32 s19, s8, 0x5800
	s_add_i32 s18, s9, -2
	s_add_i32 s20, s19, 0xffffa800
	s_mul_hi_i32 s18, s18, 0x2c00
	s_add_u32 s78, s64, s20
	s_addc_u32 s79, s65, s18
	s_add_i32 s18, s9, -1
	s_add_i32 s20, s19, 0xffffd400
	s_mul_hi_i32 s18, s18, 0x2c00
	s_add_u32 s80, s64, s20
	s_addc_u32 s81, s65, s18
	s_mul_hi_i32 s18, s9, 0x2c00
	s_add_u32 s82, s58, s19
	s_addc_u32 s83, s59, s18
	s_or_b32 s9, s9, 1
	s_mul_hi_i32 s20, s9, 0x2c00
	s_mulk_i32 s9, 0x2c00
	s_add_u32 s84, s58, s9
	s_addc_u32 s85, s59, s20
	s_add_u32 s86, s94, s19
	s_addc_u32 s87, s95, s18
	s_add_u32 vcc_lo, s94, s9
	s_addc_u32 vcc_hi, s95, s20
	s_lshl_b32 s9, s8, 8
	s_mul_i32 s8, s8, 0x160000
	s_mul_hi_i32 s19, s9, 0x1600
	s_add_u32 s18, s50, s8
	s_addc_u32 s19, s51, s19
	s_or_b32 s8, s9, 1
	s_mul_hi_i32 s9, s8, 0x1600
	s_mulk_i32 s8, 0x1600
	s_add_u32 s36, s50, s8
	s_addc_u32 s37, s51, s9
	v_readlane_b32 s100, v249, 40
	v_readlane_b32 s101, v249, 41
	v_readlane_b32 s12, v249, 36
	v_readlane_b32 s13, v249, 37
	s_mov_b64 s[98:99], vcc
	v_readfirstlane_b32 s8, v210
	v_lshlrev_b32_e32 v1, 4, v210
	v_add_u32_e32 v2, 0x2c00, v1
	v_add_u32_e32 v3, 0x5800, v1
	v_lshlrev_b32_e32 v7, 3, v210
	s_nop 3
	s_lshr_b32 s8, s8, 6
	global_load_dwordx4 v[68:71], v1, s[78:79]
	global_load_dwordx4 v[72:75], v1, s[80:81]
	global_load_dwordx4 v[76:79], v1, s[82:83]
	global_load_dwordx4 v[80:83], v1, s[84:85]
	global_load_dwordx4 v[84:87], v1, s[86:87]
	global_load_dwordx4 v[88:91], v1, s[98:99]
	global_load_dwordx4 v[92:95], v1, s[100:101]
	global_load_dwordx4 v[96:99], v2, s[100:101]
	global_load_dwordx4 v[100:103], v3, s[100:101]
	global_load_dwordx4 v[104:107], v1, s[12:13]
	s_cmp_lt_u32 s8, 3
	s_cbranch_scc0 .Lcf_nok1
	v_add_u32_e32 v4, 0x2000, v1
	v_add_u32_e32 v5, 0x2000, v2
	v_add_u32_e32 v6, 0x2000, v3
	v_add_u32_e32 v8, 0x1000, v7
	global_load_dwordx4 v[108:111], v4, s[78:79]
	global_load_dwordx4 v[112:115], v4, s[80:81]
	global_load_dwordx4 v[116:119], v4, s[82:83]
	global_load_dwordx4 v[120:123], v4, s[84:85]
	global_load_dwordx4 v[124:127], v4, s[86:87]
	global_load_dwordx4 v[128:131], v4, s[98:99]
	global_load_dwordx4 v[132:135], v4, s[100:101]
	global_load_dwordx4 v[136:139], v5, s[100:101]
	global_load_dwordx4 v[140:143], v6, s[100:101]
	global_load_dwordx4 v[144:147], v4, s[12:13]
; __device__ __forceinline__ unsigned cvt_pk_bf16(float lo, float hi) { const f32x2 v = {lo, hi}; const bf16x2_t b = __builtin_convertvector(v, bf16x2_t); return __builtin_bit_cast(unsigned, b); }
; __device__ __forceinline__ float silu_f(float c) { return c * __builtin_amdgcn_rcpf(1.f + __builtin_amdgcn_exp2f(-c * LOG2E)); }
; template <class Sched> __device__ __forceinline__ void conv_fixup(const Sched& S, bf16_t* U, const float* bot, const float* topa, const float* topv, const float* cw, const float* cb) {
;     ...
;         for (int k = 0; k < NIT; ++k) {
;             const int f = tid + 512 * k;
;             const float c0 = v[k][0] * v[k][6] + v[k][1] * v[k][7] + v[k][2] * v[k][8] + v[k][9], c1 = v[k][1] * v[k][6] + v[k][2] * v[k][7] + v[k][3] * v[k][8] + v[k][9];
;             const unsigned r0 = cvt_pk_bf16(silu_f(c0) * v[k][4], 0.f), r1 = cvt_pk_bf16(silu_f(c1) * v[k][5], 0.f);
;             if (f < FF) { U[(size_t)(u.pm * 256) * FF + f] = (bf16_t)(r0 & 0xffffu); U[(size_t)(u.pm * 256 + 1) * FF + f] = (bf16_t)(r1 & 0xffffu); }
;         }
.Lcf_nok1:
	s_waitcnt vmcnt(0)
	v_mul_f32_e32 v9, v92, v68
	v_mul_f32_e32 v13, v92, v72
	v_mul_f32_e32 v10, v93, v69
	v_mul_f32_e32 v14, v93, v73
	v_mul_f32_e32 v11, v94, v70
	v_mul_f32_e32 v15, v94, v74
	v_mul_f32_e32 v12, v95, v71
	v_mul_f32_e32 v16, v95, v75
	v_fmac_f32_e32 v9, v96, v72
	v_fmac_f32_e32 v13, v96, v76
	v_fmac_f32_e32 v10, v97, v73
	v_fmac_f32_e32 v14, v97, v77
	v_fmac_f32_e32 v11, v98, v74
	v_fmac_f32_e32 v15, v98, v78
	v_fmac_f32_e32 v12, v99, v75
	v_fmac_f32_e32 v16, v99, v79
	v_fmac_f32_e32 v9, v100, v76
	v_fmac_f32_e32 v13, v100, v80
	v_fmac_f32_e32 v10, v101, v77
	v_fmac_f32_e32 v14, v101, v81
	v_fmac_f32_e32 v11, v102, v78
	v_fmac_f32_e32 v15, v102, v82
	v_fmac_f32_e32 v12, v103, v79
	v_fmac_f32_e32 v16, v103, v83
	v_add_f32_e32 v9, v104, v9
	v_add_f32_e32 v13, v104, v13
	v_add_f32_e32 v10, v105, v10
	v_add_f32_e32 v14, v105, v14
	v_add_f32_e32 v11, v106, v11
	v_add_f32_e32 v15, v106, v15
	v_add_f32_e32 v12, v107, v12
	v_add_f32_e32 v16, v107, v16
	v_mul_f32_e32 v17, 0xbfb8aa3b, v9
	v_mul_f32_e32 v18, 0xbfb8aa3b, v10
	v_mul_f32_e32 v19, 0xbfb8aa3b, v11
	v_mul_f32_e32 v20, 0xbfb8aa3b, v12
	v_mul_f32_e32 v21, 0xbfb8aa3b, v13
	v_mul_f32_e32 v22, 0xbfb8aa3b, v14
	v_mul_f32_e32 v23, 0xbfb8aa3b, v15
	v_mul_f32_e32 v24, 0xbfb8aa3b, v16
	v_exp_f32_e32 v17, v17
	v_exp_f32_e32 v18, v18
	v_exp_f32_e32 v19, v19
	v_exp_f32_e32 v20, v20
	v_exp_f32_e32 v21, v21
	v_exp_f32_e32 v22, v22
	v_exp_f32_e32 v23, v23
	v_exp_f32_e32 v24, v24
	v_add_f32_e32 v17, 1.0, v17
	v_add_f32_e32 v18, 1.0, v18
	v_add_f32_e32 v19, 1.0, v19
	v_add_f32_e32 v20, 1.0, v20
	v_add_f32_e32 v21, 1.0, v21
	v_add_f32_e32 v22, 1.0, v22
	v_add_f32_e32 v23, 1.0, v23
	v_add_f32_e32 v24, 1.0, v24
	v_rcp_f32_e32 v17, v17
	v_rcp_f32_e32 v18, v18
	v_rcp_f32_e32 v19, v19
	v_rcp_f32_e32 v20, v20
	v_rcp_f32_e32 v21, v21
	v_rcp_f32_e32 v22, v22
	v_rcp_f32_e32 v23, v23
	v_rcp_f32_e32 v24, v24
	v_mul_f32_e32 v9, v9, v17
	v_mul_f32_e32 v10, v10, v18
	v_mul_f32_e32 v11, v11, v19
	v_mul_f32_e32 v12, v12, v20
	v_mul_f32_e32 v13, v13, v21
	v_mul_f32_e32 v14, v14, v22
	v_mul_f32_e32 v15, v15, v23
	v_mul_f32_e32 v16, v16, v24
	v_mul_f32_e32 v9, v84, v9
	v_mul_f32_e32 v13, v88, v13
	v_mul_f32_e32 v10, v85, v10
	v_mul_f32_e32 v14, v89, v14
	v_mul_f32_e32 v11, v86, v11
	v_mul_f32_e32 v15, v90, v15
	v_mul_f32_e32 v12, v87, v12
	v_mul_f32_e32 v16, v91, v16
	v_cvt_pk_bf16_f32 v26, v9, v10
	v_cvt_pk_bf16_f32 v27, v11, v12
	v_cvt_pk_bf16_f32 v28, v13, v14
	v_cvt_pk_bf16_f32 v29, v15, v16
	global_store_dwordx2 v7, v[26:27], s[18:19]
	global_store_dwordx2 v7, v[28:29], s[36:37]
	s_cmp_lt_u32 s8, 3
	s_cbranch_scc0 .Lcf_done
	v_mul_f32_e32 v9, v132, v108
	v_mul_f32_e32 v13, v132, v112
	v_mul_f32_e32 v10, v133, v109
	v_mul_f32_e32 v14, v133, v113
	v_mul_f32_e32 v11, v134, v110
	v_mul_f32_e32 v15, v134, v114
	v_mul_f32_e32 v12, v135, v111
	v_mul_f32_e32 v16, v135, v115
	v_fmac_f32_e32 v9, v136, v112
	v_fmac_f32_e32 v13, v136, v116
	v_fmac_f32_e32 v10, v137, v113
	v_fmac_f32_e32 v14, v137, v117
	v_fmac_f32_e32 v11, v138, v114
	v_fmac_f32_e32 v15, v138, v118
	v_fmac_f32_e32 v12, v139, v115
	v_fmac_f32_e32 v16, v139, v119
	v_fmac_f32_e32 v9, v140, v116
	v_fmac_f32_e32 v13, v140, v120
	v_fmac_f32_e32 v10, v141, v117
	v_fmac_f32_e32 v14, v141, v121
	v_fmac_f32_e32 v11, v142, v118
	v_fmac_f32_e32 v15, v142, v122
	v_fmac_f32_e32 v12, v143, v119
	v_fmac_f32_e32 v16, v143, v123
	v_add_f32_e32 v9, v144, v9
	v_add_f32_e32 v13, v144, v13
	v_add_f32_e32 v10, v145, v10
	v_add_f32_e32 v14, v145, v14
	v_add_f32_e32 v11, v146, v11
	v_add_f32_e32 v15, v146, v15
	v_add_f32_e32 v12, v147, v12
	v_add_f32_e32 v16, v147, v16
	v_mul_f32_e32 v17, 0xbfb8aa3b, v9
	v_mul_f32_e32 v18, 0xbfb8aa3b, v10
	v_mul_f32_e32 v19, 0xbfb8aa3b, v11
	v_mul_f32_e32 v20, 0xbfb8aa3b, v12
	v_mul_f32_e32 v21, 0xbfb8aa3b, v13
	v_mul_f32_e32 v22, 0xbfb8aa3b, v14
	v_mul_f32_e32 v23, 0xbfb8aa3b, v15
	v_mul_f32_e32 v24, 0xbfb8aa3b, v16
	v_exp_f32_e32 v17, v17
	v_exp_f32_e32 v18, v18
	v_exp_f32_e32 v19, v19
	v_exp_f32_e32 v20, v20
	v_exp_f32_e32 v21, v21
	v_exp_f32_e32 v22, v22
	v_exp_f32_e32 v23, v23
	v_exp_f32_e32 v24, v24
	v_add_f32_e32 v17, 1.0, v17
	v_add_f32_e32 v18, 1.0, v18
	v_add_f32_e32 v19, 1.0, v19
	v_add_f32_e32 v20, 1.0, v20
	v_add_f32_e32 v21, 1.0, v21
	v_add_f32_e32 v22, 1.0, v22
	v_add_f32_e32 v23, 1.0, v23
	v_add_f32_e32 v24, 1.0, v24
	v_rcp_f32_e32 v17, v17
	v_rcp_f32_e32 v18, v18
	v_rcp_f32_e32 v19, v19
	v_rcp_f32_e32 v20, v20
	v_rcp_f32_e32 v21, v21
	v_rcp_f32_e32 v22, v22
	v_rcp_f32_e32 v23, v23
	v_rcp_f32_e32 v24, v24
	v_mul_f32_e32 v9, v9, v17
	v_mul_f32_e32 v10, v10, v18
	v_mul_f32_e32 v11, v11, v19
	v_mul_f32_e32 v12, v12, v20
	v_mul_f32_e32 v13, v13, v21
	v_mul_f32_e32 v14, v14, v22
	v_mul_f32_e32 v15, v15, v23
	v_mul_f32_e32 v16, v16, v24
	v_mul_f32_e32 v9, v124, v9
	v_mul_f32_e32 v13, v128, v13
	v_mul_f32_e32 v10, v125, v10
	v_mul_f32_e32 v14, v129, v14
	v_mul_f32_e32 v11, v126, v11
	v_mul_f32_e32 v15, v130, v15
	v_mul_f32_e32 v12, v127, v12
	v_mul_f32_e32 v16, v131, v16
	v_cvt_pk_bf16_f32 v26, v9, v10
	v_cvt_pk_bf16_f32 v27, v11, v12
	v_cvt_pk_bf16_f32 v28, v13, v14
	v_cvt_pk_bf16_f32 v29, v15, v16
	global_store_dwordx2 v8, v[26:27], s[18:19]
	global_store_dwordx2 v8, v[28:29], s[36:37]
.Lcf_done:
	s_branch .LBB0_297
.LBB0_317:
	s_waitcnt vmcnt(0)
	v_readlane_b32 s72, v251, 63
	s_waitcnt vmcnt(63) expcnt(7) lgkmcnt(15)
	s_barrier
	s_mov_b64 s[0:1], 0
	s_mov_b64 s[18:19], -1
	v_readlane_b32 s73, v252, 0
